# convert_weights: small matrices start at rotated wave indices (max 6 instead of 9 sequential items per wave)
# speedup vs baseline: 1.0034x; 1.0034x over previous
; #define LAS __attribute__((address_space(3)))
; DI void transpose_item(const float* W, int K, int N, bf16_t* WT, int item, LAS float* scr, int lane) {
;     const int nblk = N / 32, kb = item / nblk, nb = item % nblk, k0 = 64 * kb, n0 = 32 * nb;
;     float tv[32];
; #pragma unroll
;     for (int i = 0; i < 32; ++i) { const int kk = 2 * i + (lane >> 5); tv[i] = __builtin_nontemporal_load(W + (size_t)(k0 + kk) * N + n0 + (lane & 31)); }
; #pragma unroll
;     for (int i = 0; i < 32; ++i) { const int kk = 2 * i + (lane >> 5); scr[kk * 33 + (lane & 31)] = tv[i]; }
; DI void convert_weights(const Inputs& in, int l, unsigned char* ws, LAS unsigned char* lds, int gw, int NGW, int wave, int lane) {
;     ...
;     for (int it = gw; it < I_IN; it += NGW) transpose_item(in.w_in + (size_t)l * 1024 * INC, 1024, INC, (bf16_t*)(wb + WB_IN), it, scr, lane);
;     for (int it = gw; it < 3 * I_BR; it += NGW) { const int br = it / I_BR; transpose_item(in.w_branch + (size_t)l * 1536 * 1024 + (size_t)br * 512 * 1024, 512, 1024, (bf16_t*)(wb + WB_BR) + (size_t)br * 1024 * 512, it % I_BR, scr, lane); }
.LBB0_18:
	s_add_i32 s40, s40, 256
	s_and_b32 s40, s40, 0x7ff
	s_cmpk_gt_i32 s40, 0x2ff
	v_and_b32_e32 v2, 31, v52
	s_cbranch_scc1 .LBB0_21
	v_lshl_add_u32 v7, v2, 2, s41
	v_mul_u32_u24_e32 v13, 0x84, v10
	v_and_b32_e32 v6, 56, v50
	s_waitcnt lgkmcnt(0)
	s_add_u32 s0, s14, 0x2000000
	v_mov_b32_e32 v5, 0
	v_mul_u32_u24_e32 v3, 0x84, v6
	v_lshlrev_b32_e32 v4, 2, v11
	v_add_u32_e32 v13, v7, v13
	s_addc_u32 s1, s15, 0
	v_add3_u32 v3, s41, v3, v4
	v_or_b32_e32 v8, 8, v11
	v_or_b32_e32 v9, 16, v11
	v_or_b32_e32 v12, 24, v11
	v_lshlrev_b32_e32 v4, 2, v2
	v_lshlrev_b32_e32 v6, 1, v6
	v_mov_b32_e32 v7, v5
	v_add_u32_e32 v14, 0x400, v13
	v_add_u32_e32 v15, 0x800, v13
	v_add_u32_e32 v16, 0xc00, v13
	v_add_u32_e32 v17, 0x1000, v13
	v_add_u32_e32 v18, 0x1400, v13
	v_add_u32_e32 v19, 0x1800, v13
	v_add_u32_e32 v20, 0x1c00, v13
	s_mov_b32 s50, s40

; #define LAS __attribute__((address_space(3)))
; DI void transpose_item(const float* W, int K, int N, bf16_t* WT, int item, LAS float* scr, int lane) {
;     const int nblk = N / 32, kb = item / nblk, nb = item % nblk, k0 = 64 * kb, n0 = 32 * nb;
;     float tv[32];
; #pragma unroll
;     for (int i = 0; i < 32; ++i) { const int kk = 2 * i + (lane >> 5); tv[i] = __builtin_nontemporal_load(W + (size_t)(k0 + kk) * N + n0 + (lane & 31)); }
; #pragma unroll
;     for (int i = 0; i < 32; ++i) { const int kk = 2 * i + (lane >> 5); scr[kk * 33 + (lane & 31)] = tv[i]; }
; DI void convert_weights(const Inputs& in, int l, unsigned char* ws, LAS unsigned char* lds, int gw, int NGW, int wave, int lane) {
;     ...
;     for (int it = gw; it < I_SQ; it += NGW) transpose_item(in.w_out + (size_t)l * 1024 * 1024, 1024, 1024, (bf16_t*)(wb + WB_OUT), it, scr, lane);
;     for (int it = gw; it < I_SQ; it += NGW) transpose_item(in.w_xq + (size_t)l * 1024 * 1024, 1024, 1024, (bf16_t*)(wb + WB_XQ), it, scr, lane);
.LBB0_21:
	s_add_i32 s40, s40, 1280
	s_and_b32 s40, s40, 0x7ff
	s_cmpk_lt_i32 s40, 0x200
	s_cselect_b64 s[2:3], -1, 0
	s_cmpk_gt_i32 s40, 0x1ff
	s_cbranch_scc1 .LBB0_26
	v_and_b32_e32 v4, 56, v50
	v_mov_b32_e32 v9, 0
	v_lshlrev_b32_e32 v12, 2, v2
	v_lshlrev_b32_e32 v8, 1, v4
	v_add_u32_e32 v5, s41, v12
	v_mul_u32_u24_e32 v14, 0x84, v10
	v_mul_u32_u24_e32 v3, 0x84, v4
	s_waitcnt lgkmcnt(0)
	v_lshl_add_u64 v[6:7], s[14:15], 0, v[8:9]
	s_mov_b64 s[0:1], 0x2300000
	v_lshlrev_b32_e32 v8, 2, v11
	v_mov_b32_e32 v13, v9
	v_lshl_add_u64 v[6:7], v[6:7], 0, s[0:1]
	v_add3_u32 v3, s41, v3, v8
	v_lshl_add_u64 v[8:9], s[30:31], 0, v[12:13]
	s_lshl_b32 s0, s40, 5
	v_add_u32_e32 v12, v5, v14
	s_lshl_b32 s1, s33, 5
	v_add_u32_e32 v5, 0x400, v12
	v_add_u32_e32 v13, 0x800, v12
	v_add_u32_e32 v14, 0xc00, v12
	v_add_u32_e32 v15, 0x1000, v12
	v_add_u32_e32 v16, 0x1400, v12
	v_add_u32_e32 v17, 0x1800, v12
	v_add_u32_e32 v18, 0x1c00, v12
	s_mov_b32 s48, s0
	s_mov_b32 s49, s40

; #define LAS __attribute__((address_space(3)))
; DI void transpose_item(const float* W, int K, int N, bf16_t* WT, int item, LAS float* scr, int lane) {
;     const int nblk = N / 32, kb = item / nblk, nb = item % nblk, k0 = 64 * kb, n0 = 32 * nb;
;     float tv[32];
; #pragma unroll
;     for (int i = 0; i < 32; ++i) { const int kk = 2 * i + (lane >> 5); tv[i] = __builtin_nontemporal_load(W + (size_t)(k0 + kk) * N + n0 + (lane & 31)); }
; #pragma unroll
;     for (int i = 0; i < 32; ++i) { const int kk = 2 * i + (lane >> 5); scr[kk * 33 + (lane & 31)] = tv[i]; }
; DI void convert_weights(const Inputs& in, int l, unsigned char* ws, LAS unsigned char* lds, int gw, int NGW, int wave, int lane) {
;     ...
;     for (int it = gw; it < I_KV; it += NGW) transpose_item(in.w_xkv + (size_t)l * 1024 * 2048, 1024, 2048, (bf16_t*)(wb + WB_XKV), it, scr, lane);
.LBB0_26:
	s_add_i32 s40, s40, 1024
	s_and_b32 s40, s40, 0x7ff
	s_cmpk_gt_i32 s40, 0x3ff
	s_cbranch_scc1 .LBB0_29
	v_and_b32_e32 v6, 0x7c, v54
	v_and_b32_e32 v3, 56, v50
	v_add_u32_e32 v12, s41, v6
	v_mul_u32_u24_e32 v13, 0x84, v10
	v_mul_u32_u24_e32 v7, 0x84, v3
	v_lshlrev_b32_e32 v8, 1, v3
	v_mov_b32_e32 v9, 0
	v_lshlrev_b32_e32 v3, 2, v11
	s_waitcnt lgkmcnt(0)
	v_lshl_add_u64 v[4:5], s[14:15], 0, v[8:9]
	s_mov_b64 s[0:1], 0x2700000
	v_add3_u32 v3, s41, v7, v3
	v_mov_b32_e32 v7, v9
	v_add_u32_e32 v8, v12, v13
	v_lshl_add_u64 v[4:5], v[4:5], 0, s[0:1]
	v_lshl_add_u64 v[6:7], s[6:7], 0, v[6:7]
	s_lshl_b32 s0, s40, 5
	s_lshl_b32 s1, s33, 5
	v_add_u32_e32 v9, 0x400, v8
	v_add_u32_e32 v12, 0x800, v8
	v_add_u32_e32 v13, 0xc00, v8
	v_add_u32_e32 v14, 0x1000, v8
	v_add_u32_e32 v15, 0x1400, v8
	v_add_u32_e32 v16, 0x1800, v8
	v_add_u32_e32 v17, 0x1c00, v8
	s_mov_b32 s28, s40

; #define LAS __attribute__((address_space(3)))
; DI void transpose_item(const float* W, int K, int N, bf16_t* WT, int item, LAS float* scr, int lane) {
;     const int nblk = N / 32, kb = item / nblk, nb = item % nblk, k0 = 64 * kb, n0 = 32 * nb;
;     float tv[32];
; #pragma unroll
;     for (int i = 0; i < 32; ++i) { const int kk = 2 * i + (lane >> 5); tv[i] = __builtin_nontemporal_load(W + (size_t)(k0 + kk) * N + n0 + (lane & 31)); }
; #pragma unroll
;     for (int i = 0; i < 32; ++i) { const int kk = 2 * i + (lane >> 5); scr[kk * 33 + (lane & 31)] = tv[i]; }
; DI void convert_weights(const Inputs& in, int l, unsigned char* ws, LAS unsigned char* lds, int gw, int NGW, int wave, int lane) {
;     ...
;     for (int it = gw; it < I_SQ; it += NGW) transpose_item(in.w_xo + (size_t)l * 1024 * 1024, 1024, 1024, (bf16_t*)(wb + WB_XO), it, scr, lane);
.LBB0_29:
	s_add_i32 s40, s40, 512
	s_and_b32 s40, s40, 0x7ff
	s_cmpk_lt_i32 s40, 0x200
	s_cselect_b64 s[2:3], -1, 0
	s_andn2_b64 vcc, exec, s[2:3]
	s_cbranch_vccnz .LBB0_32
	v_and_b32_e32 v6, 0x7c, v54
	v_and_b32_e32 v3, 56, v50
	v_add_u32_e32 v12, s41, v6
	v_mul_u32_u24_e32 v13, 0x84, v10
	v_mul_u32_u24_e32 v7, 0x84, v3
	v_lshlrev_b32_e32 v8, 1, v3
	v_mov_b32_e32 v9, 0
	v_lshlrev_b32_e32 v3, 2, v11
	s_waitcnt lgkmcnt(0)
	v_lshl_add_u64 v[4:5], s[14:15], 0, v[8:9]
	s_mov_b64 s[0:1], 0x2b00000
	v_add3_u32 v3, s41, v7, v3
	v_mov_b32_e32 v7, v9
	v_add_u32_e32 v8, v12, v13
	v_lshl_add_u64 v[4:5], v[4:5], 0, s[0:1]
	v_lshl_add_u64 v[6:7], s[46:47], 0, v[6:7]
	s_lshl_b32 s0, s40, 5
	s_lshl_b32 s1, s33, 5
	v_add_u32_e32 v9, 0x400, v8
	v_add_u32_e32 v12, 0x800, v8
	v_add_u32_e32 v13, 0xc00, v8
	v_add_u32_e32 v14, 0x1000, v8
	v_add_u32_e32 v15, 0x1400, v8
	v_add_u32_e32 v16, 0x1800, v8
	v_add_u32_e32 v17, 0x1c00, v8
	s_mov_b32 s6, s40

; #define LAS __attribute__((address_space(3)))
; DI void transpose_item(const float* W, int K, int N, bf16_t* WT, int item, LAS float* scr, int lane) {
;     const int nblk = N / 32, kb = item / nblk, nb = item % nblk, k0 = 64 * kb, n0 = 32 * nb;
;     float tv[32];
; #pragma unroll
;     for (int i = 0; i < 32; ++i) { const int kk = 2 * i + (lane >> 5); tv[i] = __builtin_nontemporal_load(W + (size_t)(k0 + kk) * N + n0 + (lane & 31)); }
; #pragma unroll
;     for (int i = 0; i < 32; ++i) { const int kk = 2 * i + (lane >> 5); scr[kk * 33 + (lane & 31)] = tv[i]; }
; DI void convert_weights(const Inputs& in, int l, unsigned char* ws, LAS unsigned char* lds, int gw, int NGW, int wave, int lane) {
;     ...
;     for (int it = gw; it < I_F1; it += NGW) transpose_item(in.w_ff1 + (size_t)l * 1024 * 4096, 1024, 4096, (bf16_t*)(wb + WB_F1), it, scr, lane);
.LBB0_32:
	s_add_i32 s40, s40, 1024
	s_and_b32 s40, s40, 0x7ff
	s_cmpk_gt_i32 s40, 0x7ff
	s_cbranch_scc1 .LBB0_37
	v_and_b32_e32 v4, 56, v50
	v_mov_b32_e32 v9, 0
	v_lshlrev_b32_e32 v14, 2, v2
	v_lshlrev_b32_e32 v8, 1, v4
	v_add_u32_e32 v3, s41, v14
	v_mul_u32_u24_e32 v5, 0x84, v10
	s_waitcnt lgkmcnt(0)
	v_lshl_add_u64 v[6:7], s[14:15], 0, v[8:9]
	s_mov_b64 s[0:1], 0x2d00000
	v_mul_u32_u24_e32 v12, 0x84, v4
	v_lshl_add_u64 v[6:7], v[6:7], 0, s[0:1]
	v_lshlrev_b32_e32 v8, 2, v11
	v_mov_b32_e32 v15, v9
	s_lshl_b32 s0, s40, 5
	v_add_u32_e32 v13, v3, v5
	v_add3_u32 v12, s41, v12, v8
	v_lshl_add_u64 v[8:9], s[8:9], 0, v[14:15]
	s_lshl_b32 s1, s33, 5
	v_add_u32_e32 v3, 0x400, v13
	v_add_u32_e32 v5, 0x800, v13
	v_add_u32_e32 v14, 0xc00, v13
	v_add_u32_e32 v15, 0x1000, v13
	v_add_u32_e32 v16, 0x1400, v13
	v_add_u32_e32 v17, 0x1800, v13
	v_add_u32_e32 v18, 0x1c00, v13
	s_mov_b32 s6, s0
	s_mov_b32 s7, s40

; #define LAS __attribute__((address_space(3)))
; DI void transpose_item(const float* W, int K, int N, bf16_t* WT, int item, LAS float* scr, int lane) {
;     const int nblk = N / 32, kb = item / nblk, nb = item % nblk, k0 = 64 * kb, n0 = 32 * nb;
;     float tv[32];
; #pragma unroll
;     for (int i = 0; i < 32; ++i) { const int kk = 2 * i + (lane >> 5); tv[i] = __builtin_nontemporal_load(W + (size_t)(k0 + kk) * N + n0 + (lane & 31)); }
; #pragma unroll
;     for (int i = 0; i < 32; ++i) { const int kk = 2 * i + (lane >> 5); scr[kk * 33 + (lane & 31)] = tv[i]; }
; DI void convert_weights(const Inputs& in, int l, unsigned char* ws, LAS unsigned char* lds, int gw, int NGW, int wave, int lane) {
;     ...
;     for (int it = gw; it < I_IN; it += NGW) transpose_item(in.w_in + (size_t)l * 1024 * INC, 1024, INC, (bf16_t*)(wb + WB_IN), it, scr, lane);
;     for (int it = gw; it < 3 * I_BR; it += NGW) { const int br = it / I_BR; transpose_item(in.w_branch + (size_t)l * 1536 * 1024 + (size_t)br * 512 * 1024, 512, 1024, (bf16_t*)(wb + WB_BR) + (size_t)br * 1024 * 512, it % I_BR, scr, lane); }
.LBB0_1598:
	s_add_i32 s36, s36, 256
	s_and_b32 s36, s36, 0x7ff
	s_cmpk_gt_i32 s36, 0x2ff
	v_and_b32_e32 v6, 31, v48
	s_cbranch_scc1 .LBB0_1601
	s_add_u32 s16, s34, 0x2000000
	s_mul_i32 s2, s44, 0x600000
	s_addc_u32 s17, s35, 0
	v_lshl_add_u32 v0, v6, 2, s22
	v_mul_u32_u24_e32 v1, 0x84, v4
	s_add_u32 s23, s28, s2
	v_add3_u32 v7, s22, v1, v70
	v_or_b32_e32 v9, 8, v51
	v_or_b32_e32 v14, 16, v51
	v_or_b32_e32 v15, 24, v51
	s_addc_u32 s28, s29, 0
	v_lshlrev_b32_e32 v176, 2, v6
	v_add_u32_e32 v16, v0, v5
	v_lshlrev_b32_e32 v10, 1, v4
	s_mov_b32 s29, s36

; #define LAS __attribute__((address_space(3)))
; DI void transpose_item(const float* W, int K, int N, bf16_t* WT, int item, LAS float* scr, int lane) {
;     const int nblk = N / 32, kb = item / nblk, nb = item % nblk, k0 = 64 * kb, n0 = 32 * nb;
;     float tv[32];
; #pragma unroll
;     for (int i = 0; i < 32; ++i) { const int kk = 2 * i + (lane >> 5); tv[i] = __builtin_nontemporal_load(W + (size_t)(k0 + kk) * N + n0 + (lane & 31)); }
; #pragma unroll
;     for (int i = 0; i < 32; ++i) { const int kk = 2 * i + (lane >> 5); scr[kk * 33 + (lane & 31)] = tv[i]; }
; DI void convert_weights(const Inputs& in, int l, unsigned char* ws, LAS unsigned char* lds, int gw, int NGW, int wave, int lane) {
;     ...
;     for (int it = gw; it < I_SQ; it += NGW) transpose_item(in.w_out + (size_t)l * 1024 * 1024, 1024, 1024, (bf16_t*)(wb + WB_OUT), it, scr, lane);
;     for (int it = gw; it < I_SQ; it += NGW) transpose_item(in.w_xq + (size_t)l * 1024 * 1024, 1024, 1024, (bf16_t*)(wb + WB_XQ), it, scr, lane);
.LBB0_1601:
	s_add_i32 s36, s36, 1280
	s_and_b32 s36, s36, 0x7ff
	s_cmpk_lt_i32 s36, 0x200
	s_cselect_b64 s[2:3], -1, 0
	s_cmpk_gt_i32 s36, 0x1ff
	v_lshlrev_b32_e32 v0, 2, v6
	s_cbranch_scc1 .LBB0_1606
	v_lshlrev_b32_e32 v176, 1, v4
	s_lshl_b32 s29, s44, 22
	v_lshl_add_u64 v[2:3], s[34:35], 0, v[176:177]
	s_mov_b64 s[4:5], 0x2300000
	v_mul_u32_u24_e32 v1, 0x84, v4
	v_lshl_add_u64 v[2:3], v[2:3], 0, s[4:5]
	s_add_u32 s4, s30, s29
	v_add_u32_e32 v9, s22, v0
	v_add3_u32 v7, s22, v1, v70
	s_addc_u32 s5, s31, 0
	v_mov_b32_e32 v1, v177
	s_lshl_b32 s23, s36, 5
	v_lshl_add_u64 v[10:11], s[4:5], 0, v[0:1]
	s_lshl_b32 s28, s38, 5
	v_add_u32_e32 v1, v9, v5
	s_mov_b32 s30, s23
	s_mov_b32 s31, s36

; #define LAS __attribute__((address_space(3)))
; DI void transpose_item(const float* W, int K, int N, bf16_t* WT, int item, LAS float* scr, int lane) {
;     const int nblk = N / 32, kb = item / nblk, nb = item % nblk, k0 = 64 * kb, n0 = 32 * nb;
;     float tv[32];
; #pragma unroll
;     for (int i = 0; i < 32; ++i) { const int kk = 2 * i + (lane >> 5); tv[i] = __builtin_nontemporal_load(W + (size_t)(k0 + kk) * N + n0 + (lane & 31)); }
; #pragma unroll
;     for (int i = 0; i < 32; ++i) { const int kk = 2 * i + (lane >> 5); scr[kk * 33 + (lane & 31)] = tv[i]; }
; DI void convert_weights(const Inputs& in, int l, unsigned char* ws, LAS unsigned char* lds, int gw, int NGW, int wave, int lane) {
;     ...
;     for (int it = gw; it < I_KV; it += NGW) transpose_item(in.w_xkv + (size_t)l * 1024 * 2048, 1024, 2048, (bf16_t*)(wb + WB_XKV), it, scr, lane);
.LBB0_1606:
	s_add_i32 s36, s36, 1024
	s_and_b32 s36, s36, 0x7ff
	s_cmpk_gt_i32 s36, 0x3ff
	s_cbranch_scc1 .LBB0_1609
	v_lshlrev_b32_e32 v176, 1, v4
	s_lshl_b32 s16, s44, 23
	v_lshl_add_u64 v[2:3], s[34:35], 0, v[176:177]
	s_mov_b64 s[4:5], 0x2700000
	v_lshl_add_u64 v[2:3], v[2:3], 0, s[4:5]
	s_add_u32 s4, s26, s16
	v_add_u32_e32 v7, s22, v8
	v_mul_u32_u24_e32 v1, 0x84, v4
	s_addc_u32 s5, s27, 0
	v_mov_b32_e32 v9, v177
	v_add3_u32 v1, s22, v1, v70
	v_lshl_add_u64 v[10:11], s[4:5], 0, v[8:9]
	s_lshl_b32 s23, s36, 5
	s_lshl_b32 s24, s38, 5
	v_add_u32_e32 v7, v7, v5
	s_mov_b32 s25, s36

; #define LAS __attribute__((address_space(3)))
; DI void transpose_item(const float* W, int K, int N, bf16_t* WT, int item, LAS float* scr, int lane) {
;     const int nblk = N / 32, kb = item / nblk, nb = item % nblk, k0 = 64 * kb, n0 = 32 * nb;
;     float tv[32];
; #pragma unroll
;     for (int i = 0; i < 32; ++i) { const int kk = 2 * i + (lane >> 5); tv[i] = __builtin_nontemporal_load(W + (size_t)(k0 + kk) * N + n0 + (lane & 31)); }
; #pragma unroll
;     for (int i = 0; i < 32; ++i) { const int kk = 2 * i + (lane >> 5); scr[kk * 33 + (lane & 31)] = tv[i]; }
; DI void convert_weights(const Inputs& in, int l, unsigned char* ws, LAS unsigned char* lds, int gw, int NGW, int wave, int lane) {
;     ...
;     for (int it = gw; it < I_SQ; it += NGW) transpose_item(in.w_xo + (size_t)l * 1024 * 1024, 1024, 1024, (bf16_t*)(wb + WB_XO), it, scr, lane);
.LBB0_1609:
	s_add_i32 s36, s36, 512
	s_and_b32 s36, s36, 0x7ff
	s_cmpk_lt_i32 s36, 0x200
	s_cselect_b64 s[2:3], -1, 0
	s_andn2_b64 vcc, exec, s[2:3]
	s_cbranch_vccnz .LBB0_1612
	v_lshlrev_b32_e32 v176, 1, v4
	s_lshl_b32 s4, s44, 22
	v_lshl_add_u64 v[2:3], s[34:35], 0, v[176:177]
	s_mov_b64 s[2:3], 0x2b00000
	v_lshl_add_u64 v[2:3], v[2:3], 0, s[2:3]
	s_add_u32 s2, s40, s4
	v_add_u32_e32 v7, s22, v8
	v_mul_u32_u24_e32 v1, 0x84, v4
	s_addc_u32 s3, s41, 0
	v_mov_b32_e32 v9, v177
	v_add3_u32 v1, s22, v1, v70
	v_lshl_add_u64 v[8:9], s[2:3], 0, v[8:9]
	s_lshl_b32 s16, s36, 5
	s_lshl_b32 s17, s38, 5
	v_add_u32_e32 v7, v7, v5
	s_mov_b32 s23, s36

; #define LAS __attribute__((address_space(3)))
; DI void transpose_item(const float* W, int K, int N, bf16_t* WT, int item, LAS float* scr, int lane) {
;     const int nblk = N / 32, kb = item / nblk, nb = item % nblk, k0 = 64 * kb, n0 = 32 * nb;
;     float tv[32];
; #pragma unroll
;     for (int i = 0; i < 32; ++i) { const int kk = 2 * i + (lane >> 5); tv[i] = __builtin_nontemporal_load(W + (size_t)(k0 + kk) * N + n0 + (lane & 31)); }
; #pragma unroll
;     for (int i = 0; i < 32; ++i) { const int kk = 2 * i + (lane >> 5); scr[kk * 33 + (lane & 31)] = tv[i]; }
; DI void convert_weights(const Inputs& in, int l, unsigned char* ws, LAS unsigned char* lds, int gw, int NGW, int wave, int lane) {
;     ...
;     for (int it = gw; it < I_F1; it += NGW) transpose_item(in.w_ff1 + (size_t)l * 1024 * 4096, 1024, 4096, (bf16_t*)(wb + WB_F1), it, scr, lane);
.LBB0_1612:
	s_add_i32 s36, s36, 1024
	s_and_b32 s36, s36, 0x7ff
	s_cmpk_gt_i32 s36, 0x7ff
	s_cbranch_scc1 .LBB0_1617
	v_lshlrev_b32_e32 v176, 1, v4
	s_lshl_b32 s23, s44, 24
	v_lshl_add_u64 v[2:3], s[34:35], 0, v[176:177]
	s_mov_b64 s[2:3], 0x2d00000
	v_mul_u32_u24_e32 v1, 0x84, v4
	v_lshl_add_u64 v[2:3], v[2:3], 0, s[2:3]
	s_add_u32 s2, s18, s23
	v_add_u32_e32 v7, s22, v0
	v_add3_u32 v68, s22, v1, v70
	s_addc_u32 s3, s19, 0
	v_mov_b32_e32 v1, v177
	s_lshl_b32 s16, s36, 5
	v_lshl_add_u64 v[0:1], s[2:3], 0, v[0:1]
	s_lshl_b32 s17, s38, 5
	v_add_u32_e32 v69, v7, v5
	s_mov_b32 s18, s16
	s_mov_b32 s19, s36
